# teams staggered after the last grid barrier: each row panel's team delayed by panel_index x s_sleep 4 at P4 entry, so the store-bound P4/P6 epilogues of different teams do not coincide
# baseline (speedup 1.0000x reference)
.LBB0_545:
	s_and_b64 vcc, exec, s[62:63]
	s_cbranch_vccnz .Lstag_done
	s_and_b32 s96, s2, 7
	s_lshl_b32 s96, s96, 3
	s_bfe_u32 s97, s2, 0x30003
	s_or_b32 s96, s96, s97
.Lstag_loop:
	s_cmp_eq_u32 s96, 0
	s_cbranch_scc1 .Lstag_done
	s_sleep 4
	s_sub_u32 s96, s96, 1
	s_branch .Lstag_loop
